# stack: diff map1->map2 transition prefetch, mid-prologue vmcnt waits removed, K fragments of QK k-step 1 also hoisted behind the end-of-tile barrier (spare regs v202-209)
# speedup vs baseline: 1.0036x; 1.0036x over previous
.LBB0_132:
	s_and_b32 s5, s64, 7
	s_lshl_b32 s0, s5, 8
	s_or_b32 s22, s14, s0
	s_mov_b32 s23, s15
	s_lshl_b64 s[0:1], s[22:23], 10
	s_add_u32 s0, s55, s0
	s_addc_u32 s1, s56, s1
	s_lshl_b32 s4, s64, 4
	s_and_b32 s65, s4, 0x180
	s_lshl_b32 s4, s65, 1
	s_add_u32 s30, s0, s4
	s_addc_u32 s31, s1, 0
	s_lshl_b64 s[0:1], s[2:3], 21
	s_add_u32 s3, s57, s0
	s_addc_u32 s6, s58, s1
	s_add_u32 s24, s3, s4
	s_addc_u32 s25, s6, 0
	v_mov_b32_e32 v121, v218
	s_add_u32 s0, s90, s0
	v_mov_b32_e32 v4, v218
	s_addc_u32 s1, s91, s1
	s_add_u32 s3, s0, s4
	v_ashrrev_i32_e32 v0, 6, v4
	v_and_b32_e32 v6, 31, v4
	v_readfirstlane_b32 s0, v0
	v_lshl_or_b32 v0, v0, 5, v6
	v_ashrrev_i32_e32 v1, 31, v0
	v_lshlrev_b64 v[0:1], 10, v[0:1]
	v_lshrrev_b32_e32 v7, 1, v4
	v_and_b32_e32 v5, 63, v4
	v_lshl_add_u64 v[0:1], s[30:31], 0, v[0:1]
	v_and_b32_e32 v184, 16, v7
	s_addc_u32 s66, s1, 0
	v_lshl_add_u64 v[0:1], v[0:1], 0, v[184:185]
	s_lshl_b32 s1, s0, 10
	v_lshlrev_b32_e32 v8, 4, v5
	global_load_dwordx4 v[96:99], v[0:1], off
	global_load_dwordx4 v[100:103], v[0:1], off offset:32
	global_load_dwordx4 v[104:107], v[0:1], off offset:64
	global_load_dwordx4 v[108:111], v[0:1], off offset:96
	v_or_b32_e32 v0, s1, v8
	v_ashrrev_i32_e32 v1, 31, v0
	v_lshrrev_b32_e32 v1, 25, v1
	v_add_u32_e32 v1, v0, v1
	v_lshlrev_b32_e32 v9, 3, v5
	s_lshl_b32 s0, s0, 6
	v_ashrrev_i32_e32 v2, 7, v1
	v_and_b32_e32 v1, 0xffffff80, v1
	v_and_b32_e32 v3, 32, v4
	s_and_b32 s0, s0, 64
	v_and_b32_e32 v10, 24, v9
	v_sub_u32_e32 v0, v0, v1
	v_or3_b32 v3, v10, v3, s0
	s_ashr_i32 s0, s1, 8
	v_ashrrev_i32_e32 v0, 4, v0
	v_lshrrev_b32_e32 v1, 1, v2
	s_and_b32 s6, s0, 0x7ffff0
	s_lshr_b32 s0, s0, 1
	v_bitop3_b32 v0, v1, v0, 7 bitop3:0x6c
	v_bfe_u32 v1, v4, 2, 2
	s_and_b32 s0, s0, 4
	v_and_or_b32 v1, v7, 8, v1
	s_or_b32 s0, s6, s0
	v_or_b32_e32 v10, s0, v1
	s_add_i32 s0, s1, 0x2000
	s_ashr_i32 s0, s0, 8
	s_and_b32 s6, s0, 0x7ffff0
	s_lshr_b32 s0, s0, 1
	s_and_b32 s0, s0, 4
	s_or_b32 s0, s6, s0
	s_add_i32 s4, 0, 0x14000
	v_or_b32_e32 v1, s0, v1
	s_lshl_b32 s0, s5, 17
	s_lshl_b32 s6, s5, 18
	v_lshl_or_b32 v114, v1, 9, v3
	v_lshlrev_b32_e32 v1, 9, v2
	s_add_u32 s68, s24, s6
	v_lshl_add_u32 v0, v0, 3, v1
	s_addc_u32 s69, s25, 0
	s_add_i32 s5, s1, 0
	v_ashrrev_i32_e32 v1, 31, v0
	s_add_i32 m0, s5, 0x8000
	v_lshl_or_b32 v112, v10, 9, v3
	v_lshlrev_b64 v[0:1], 1, v[0:1]
	s_add_u32 s34, s3, s6
	v_lshl_add_u64 v[2:3], s[68:69], 0, v[0:1]
	s_addc_u32 s35, s66, 0
	v_ashrrev_i32_e32 v113, 31, v112
	s_waitcnt lgkmcnt(0)
	s_barrier
	global_load_lds_dwordx4 v[2:3], off
	v_lshl_add_u64 v[2:3], v[112:113], 1, s[34:35]
	s_mov_b32 m0, s5
	v_ashrrev_i32_e32 v115, 31, v114
	global_load_lds_dwordx4 v[2:3], off
	v_lshl_add_u64 v[2:3], v[114:115], 1, s[34:35]
	s_add_i32 m0, s5, 0x2000
	s_cmp_lg_u32 0, -1
	global_load_lds_dwordx4 v[2:3], off
	v_and_b32_e32 v2, 0x3fffffc0, v4
	v_lshl_add_u32 v119, v2, 2, s4
	v_lshlrev_b32_e32 v2, 1, v4
	s_cselect_b32 s1, 0, 0
	v_and_b32_e32 v2, 32, v2
	v_lshlrev_b32_e32 v4, 3, v4
	s_add_i32 s6, s1, 0x8000
	s_movk_i32 s54, 0x118
	v_and_b32_e32 v3, 0xc0, v8
	v_and_b32_e32 v4, 0x70, v4
	v_lshl_add_u32 v120, v6, 7, s6
	s_movk_i32 s6, 0x60
	v_lshl_add_u64 v[116:117], s[24:25], 0, v[0:1]
	v_mov_b32_e32 v194, v0
	v_lshlrev_b32_e32 v195, 1, v112
	v_lshlrev_b32_e32 v196, 1, v114
	v_and_or_b32 v0, v9, s54, v2
	v_mov_b32_e32 v14, v185
	v_mov_b32_e32 v15, v185
	v_bitop3_b32 v123, v7, v4, 16 bitop3:0x6c
	v_bitop3_b32 v124, v184, v4, 32 bitop3:0x36
	v_bitop3_b32 v125, v184, v4, 64 bitop3:0x36
	v_bitop3_b32 v126, v184, v4, s6 bitop3:0x36
	v_cmp_gt_u32_e64 s[6:7], 32, v5
	v_lshl_add_u32 v122, v6, 2, v119
	v_add3_u32 v127, v3, s1, v0
	s_or_b32 s67, s0, 0x8000
	v_mov_b32_e32 v0, v185
	v_mov_b32_e32 v1, v185
	v_mov_b32_e32 v2, v185
	v_mov_b32_e32 v3, v185
	v_mov_b32_e32 v4, v185
	v_mov_b32_e32 v5, v185
	v_mov_b32_e32 v6, v185
	v_mov_b32_e32 v7, v185
	v_mov_b32_e32 v8, v185
	v_mov_b32_e32 v9, v185
	v_mov_b32_e32 v10, v185
	v_mov_b32_e32 v11, v185
	v_mov_b32_e32 v12, v185
	v_mov_b32_e32 v13, v185
	v_mov_b64_e32 v[30:31], v[14:15]
	v_mov_b64_e32 v[46:47], v[14:15]
	v_mov_b64_e32 v[62:63], v[14:15]
	s_mov_b32 s53, 0
	v_mov_b32_e32 v128, 0
	v_mov_b32_e32 v160, 0x80000000
	v_mov_b32_e32 v161, 0x80000000
	v_mov_b32_e32 v162, 0x80000000
	v_mov_b32_e32 v163, 0x80000000
	v_mov_b32_e32 v164, 0x80000000
	v_mov_b32_e32 v165, 0x80000000
	v_mov_b32_e32 v166, 0x80000000
	v_mov_b32_e32 v167, 0x80000000
	v_mov_b32_e32 v168, 0x80000000
	v_mov_b32_e32 v169, 0x80000000
	v_mov_b32_e32 v170, 0x80000000
	v_mov_b32_e32 v171, 0x80000000
	v_mov_b32_e32 v172, 0x80000000
	v_mov_b32_e32 v173, 0x80000000
	v_mov_b32_e32 v174, 0x80000000
	v_mov_b32_e32 v175, 0x80000000
	s_mov_b32 s54, s67
	v_mov_b64_e32 v[28:29], v[12:13]
	v_mov_b64_e32 v[26:27], v[10:11]
	v_mov_b64_e32 v[24:25], v[8:9]
	v_mov_b64_e32 v[22:23], v[6:7]
	v_mov_b64_e32 v[20:21], v[4:5]
	v_mov_b64_e32 v[18:19], v[2:3]
	v_mov_b64_e32 v[16:17], v[0:1]
	v_mov_b64_e32 v[44:45], v[12:13]
	v_mov_b64_e32 v[42:43], v[10:11]
	v_mov_b64_e32 v[40:41], v[8:9]
	v_mov_b64_e32 v[38:39], v[6:7]
	v_mov_b64_e32 v[36:37], v[4:5]
	v_mov_b64_e32 v[34:35], v[2:3]
	v_mov_b64_e32 v[32:33], v[0:1]
	v_mov_b64_e32 v[60:61], v[12:13]
	v_mov_b64_e32 v[58:59], v[10:11]
	v_mov_b64_e32 v[56:57], v[8:9]
	v_mov_b64_e32 v[54:55], v[6:7]
	v_mov_b64_e32 v[52:53], v[4:5]
	v_mov_b64_e32 v[50:51], v[2:3]
	v_mov_b64_e32 v[48:49], v[0:1]
	v_mov_b32_e32 v129, 0
	s_waitcnt vmcnt(0) lgkmcnt(0)
	s_barrier
	s_and_b32 s80, s53, 1
	v_add_u32_e32 v118, v120, v123
	ds_read_b128 v[130:133], v118 offset:0
	ds_read_b128 v[134:137], v118 offset:0x1000
	v_add_u32_e32 v210, v120, v124
	ds_read_b128 v[202:205], v210 offset:0
	ds_read_b128 v[206:209], v210 offset:0x1000
	s_cmp_eq_u32 s53, 31
	s_movk_i32 s0, 0x2000
	s_cbranch_scc1 .LBB0_134

.LBB0_134:
	v_add_u32_e32 v80, s0, v120
	s_waitcnt lgkmcnt(2)
	v_add_u32_e32 v118, v80, v125
	v_add_u32_e32 v142, v80, v126
	v_mfma_f32_32x32x16_bf16 v[80:95], v[130:133], v[96:99], v[160:175]
	ds_read_b128 v[130:133], v118 offset:0
	v_mfma_f32_32x32x16_bf16 v[64:79], v[134:137], v[96:99], v[160:175]
	ds_read_b128 v[134:137], v118 offset:0x1000
	s_waitcnt lgkmcnt(2)
	v_mfma_f32_32x32x16_bf16 v[80:95], v[202:205], v[100:103], v[80:95]
	ds_read_b128 v[138:141], v142 offset:0
	v_mfma_f32_32x32x16_bf16 v[64:79], v[206:209], v[100:103], v[64:79]
	ds_read_b128 v[146:149], v142 offset:0x1000
	s_waitcnt lgkmcnt(2)
	v_mfma_f32_32x32x16_bf16 v[80:95], v[130:133], v[104:107], v[80:95]
	s_waitcnt lgkmcnt(0)
	v_mfma_f32_32x32x16_bf16 v[64:79], v[134:137], v[104:107], v[64:79]
	v_mfma_f32_32x32x16_bf16 v[80:95], v[138:141], v[108:111], v[80:95]
	s_cmp_eq_u32 s53, 0
	s_cselect_b64 s[70:71], -1, 0
	s_cmp_lg_u32 s53, 0
	v_mfma_f32_32x32x16_bf16 v[64:79], v[146:149], v[108:111], v[64:79]
	s_nop 7
	v_max_f32_e32 v118, v80, v81
	v_max3_f32 v118, v118, v82, v83
	v_max3_f32 v118, v118, v84, v85
	v_max3_f32 v118, v118, v86, v87
	v_max3_f32 v118, v118, v88, v89
	v_max3_f32 v118, v118, v90, v91
	v_max3_f32 v118, v118, v92, v93
	v_max3_f32 v118, v118, v94, v95
	v_max3_f32 v118, v118, v64, v65
	v_max3_f32 v118, v118, v66, v67
	v_max3_f32 v118, v118, v68, v69
	v_max3_f32 v118, v118, v70, v71
	v_max3_f32 v118, v118, v72, v73
	v_max3_f32 v118, v118, v74, v75
	v_max3_f32 v118, v118, v76, v77
	v_max3_f32 v118, v118, v78, v79
	s_cbranch_scc0 .Lmx1_first
	v_cmp_ge_f32_e32 vcc, s62, v118
	s_cmp_lg_u64 vcc, exec
	s_mov_b64 s[74:75], 0
	s_mov_b64 s[72:73], 0
	s_cbranch_scc1 .Lmx1_slow
	v_mov_b32_e32 v130, 1.0
	s_branch .LBB0_146

.LBB0_146:
	v_exp_f32_e32 v80, v80
	v_exp_f32_e32 v81, v81
	v_exp_f32_e32 v82, v82
	v_exp_f32_e32 v83, v83
	v_exp_f32_e32 v84, v84
	v_exp_f32_e32 v118, v64
	v_exp_f32_e32 v85, v85
	v_add_f32_e32 v64, v81, v80
	v_exp_f32_e32 v86, v86
	v_add_f32_e32 v64, v82, v64
	v_exp_f32_e32 v87, v87
	v_add_f32_e32 v64, v83, v64
	v_exp_f32_e32 v88, v88
	v_add_f32_e32 v64, v84, v64
	v_exp_f32_e32 v89, v89
	v_add_f32_e32 v64, v85, v64
	v_exp_f32_e32 v90, v90
	v_add_f32_e32 v64, v86, v64
	v_exp_f32_e32 v91, v91
	v_add_f32_e32 v64, v87, v64
	v_exp_f32_e32 v92, v92
	v_add_f32_e32 v64, v88, v64
	v_exp_f32_e32 v93, v93
	v_add_f32_e32 v64, v89, v64
	v_exp_f32_e32 v94, v94
	v_add_f32_e32 v64, v90, v64
	v_exp_f32_e32 v95, v95
	v_add_f32_e32 v64, v91, v64
	v_add_f32_e32 v64, v92, v64
	v_exp_f32_e32 v65, v65
	v_add_f32_e32 v64, v93, v64
	v_exp_f32_e32 v131, v66
	v_add_f32_e32 v64, v94, v64
	v_exp_f32_e32 v132, v67
	v_add_f32_e32 v64, v95, v64
	v_exp_f32_e32 v133, v68
	v_add_f32_e32 v64, v118, v64
	v_exp_f32_e32 v134, v69
	v_add_f32_e32 v64, v65, v64
	v_exp_f32_e32 v135, v70
	v_add_f32_e32 v64, v131, v64
	v_exp_f32_e32 v136, v71
	v_add_f32_e32 v64, v132, v64
	v_exp_f32_e32 v137, v72
	v_add_f32_e32 v64, v133, v64
	v_exp_f32_e32 v138, v73
	v_add_f32_e32 v64, v134, v64
	v_exp_f32_e32 v139, v74
	v_add_f32_e32 v64, v135, v64
	v_exp_f32_e32 v140, v75
	v_add_f32_e32 v64, v136, v64
	v_exp_f32_e32 v141, v76
	v_add_f32_e32 v64, v137, v64
	v_exp_f32_e32 v142, v77
	v_add_f32_e32 v64, v138, v64
	v_exp_f32_e32 v143, v78
	v_add_f32_e32 v64, v139, v64
	v_exp_f32_e32 v146, v79
	v_add_f32_e32 v64, v140, v64
	v_add_f32_e32 v64, v141, v64
	v_add_f32_e32 v64, v142, v64
	v_add_f32_e32 v64, v143, v64
	v_add_f32_e32 v64, v146, v64
	s_add_i32 s53, s53, 1
	v_fma_f32 v129, v129, v130, v64
	v_cvt_pk_bf16_f32 v66, v80, v81
	v_cvt_pk_bf16_f32 v67, v82, v83
	v_cvt_pk_bf16_f32 v68, v84, v85
	v_cvt_pk_bf16_f32 v69, v86, v87
	v_cvt_pk_bf16_f32 v70, v88, v89
	v_cvt_pk_bf16_f32 v71, v90, v91
	v_cvt_pk_bf16_f32 v72, v92, v93
	v_cvt_pk_bf16_f32 v73, v94, v95
	v_cvt_pk_bf16_f32 v74, v118, v65
	v_cvt_pk_bf16_f32 v75, v131, v132
	v_cvt_pk_bf16_f32 v76, v133, v134
	v_cvt_pk_bf16_f32 v77, v135, v136
	v_cvt_pk_bf16_f32 v78, v137, v138
	v_cvt_pk_bf16_f32 v79, v139, v140
	v_cvt_pk_bf16_f32 v80, v141, v142
	v_cvt_pk_bf16_f32 v81, v143, v146
	s_nop 0
	v_permlane32_swap_b32_e32 v66, v68
	v_permlane32_swap_b32_e32 v67, v69
	v_permlane32_swap_b32_e32 v70, v72
	v_permlane32_swap_b32_e32 v71, v73
	v_permlane32_swap_b32_e32 v74, v76
	v_permlane32_swap_b32_e32 v75, v77
	v_permlane32_swap_b32_e32 v78, v80
	v_permlane32_swap_b32_e32 v79, v81
	v_lshl_add_u32 v65, s80, 14, v127
	ds_read_b64_tr_b16 v[82:83], v65 offset:0
	ds_read_b64_tr_b16 v[84:85], v65 offset:0x800
	ds_read_b64_tr_b16 v[86:87], v65 offset:0x1000
	ds_read_b64_tr_b16 v[88:89], v65 offset:0x1800
	ds_read_b64_tr_b16 v[90:91], v65 offset:0x2000
	ds_read_b64_tr_b16 v[92:93], v65 offset:0x2800
	ds_read_b64_tr_b16 v[130:131], v65 offset:0x3000
	ds_read_b64_tr_b16 v[132:133], v65 offset:0x3800
	ds_read_b64_tr_b16 v[134:135], v65 offset:0x200
	ds_read_b64_tr_b16 v[136:137], v65 offset:0xa00
	ds_read_b64_tr_b16 v[138:139], v65 offset:0x1200
	ds_read_b64_tr_b16 v[140:141], v65 offset:0x1a00
	ds_read_b64_tr_b16 v[146:147], v65 offset:0x2200
	ds_read_b64_tr_b16 v[148:149], v65 offset:0x2a00
	ds_read_b64_tr_b16 v[150:151], v65 offset:0x3200
	ds_read_b64_tr_b16 v[152:153], v65 offset:0x3a00
	s_waitcnt lgkmcnt(8)
	s_nop 0
	v_mfma_f32_32x32x16_bf16 v[48:63], v[66:69], v[82:85], v[48:63]
	ds_read_b64_tr_b16 v[82:83], v65 offset:0x400
	ds_read_b64_tr_b16 v[84:85], v65 offset:0xc00
	v_mfma_f32_32x32x16_bf16 v[48:63], v[70:73], v[86:89], v[48:63]
	ds_read_b64_tr_b16 v[86:87], v65 offset:0x1400
	ds_read_b64_tr_b16 v[88:89], v65 offset:0x1c00
	v_mfma_f32_32x32x16_bf16 v[48:63], v[74:77], v[90:93], v[48:63]
	ds_read_b64_tr_b16 v[90:91], v65 offset:0x2400
	ds_read_b64_tr_b16 v[92:93], v65 offset:0x2c00
	v_mfma_f32_32x32x16_bf16 v[48:63], v[78:81], v[130:133], v[48:63]
	ds_read_b64_tr_b16 v[130:131], v65 offset:0x3400
	ds_read_b64_tr_b16 v[132:133], v65 offset:0x3c00
	s_waitcnt lgkmcnt(8)
	v_mfma_f32_32x32x16_bf16 v[32:47], v[66:69], v[134:137], v[32:47]
	ds_read_b64_tr_b16 v[134:135], v65 offset:0x600
	ds_read_b64_tr_b16 v[136:137], v65 offset:0xe00
	v_mfma_f32_32x32x16_bf16 v[32:47], v[70:73], v[138:141], v[32:47]
	ds_read_b64_tr_b16 v[138:139], v65 offset:0x1600
	ds_read_b64_tr_b16 v[140:141], v65 offset:0x1e00
	v_mfma_f32_32x32x16_bf16 v[32:47], v[74:77], v[146:149], v[32:47]
	ds_read_b64_tr_b16 v[146:147], v65 offset:0x2600
	ds_read_b64_tr_b16 v[148:149], v65 offset:0x2e00
	v_mfma_f32_32x32x16_bf16 v[32:47], v[78:81], v[150:153], v[32:47]
	ds_read_b64_tr_b16 v[150:151], v65 offset:0x3600
	ds_read_b64_tr_b16 v[152:153], v65 offset:0x3e00
	s_waitcnt lgkmcnt(8)
	v_mfma_f32_32x32x16_bf16 v[16:31], v[66:69], v[82:85], v[16:31]
	s_waitcnt lgkmcnt(0)
	v_mfma_f32_32x32x16_bf16 v[16:31], v[70:73], v[86:89], v[16:31]
	v_mfma_f32_32x32x16_bf16 v[16:31], v[74:77], v[90:93], v[16:31]
	v_mfma_f32_32x32x16_bf16 v[16:31], v[78:81], v[130:133], v[16:31]
	v_mfma_f32_32x32x16_bf16 v[0:15], v[66:69], v[134:137], v[0:15]
	s_waitcnt vmcnt(0)
	s_add_i32 s54, s54, 0x8000
	s_cmp_eq_u32 s53, 32
	s_waitcnt vmcnt(0) lgkmcnt(0)
	s_barrier
	s_and_b32 s1, s53, 1
	s_lshl_b32 s1, s1, 13
	v_add3_u32 v118, v120, v123, s1
	v_add3_u32 v210, v120, v124, s1
	ds_read_b128 v[130:133], v118 offset:0
	ds_read_b128 v[134:137], v118 offset:0x1000
	ds_read_b128 v[202:205], v210 offset:0
	ds_read_b128 v[206:209], v210 offset:0x1000
	s_cmp_eq_u32 s53, 32
	v_mfma_f32_32x32x16_bf16 v[0:15], v[70:73], v[138:141], v[0:15]
	v_mfma_f32_32x32x16_bf16 v[0:15], v[74:77], v[146:149], v[0:15]
	v_mfma_f32_32x32x16_bf16 v[0:15], v[78:81], v[150:153], v[0:15]
	s_cbranch_scc1 .LBB0_148
	s_and_b32 s80, s53, 1
	s_cmp_eq_u32 s53, 31
	s_movk_i32 s0, 0x2000
	s_cbranch_scc0 .LBB0_133
	s_branch .LBB0_134
.LBB0_148:
	v_ashrrev_i32_e32 v194, 6, v218
	v_and_b32_e32 v196, 31, v218
	v_lshl_or_b32 v194, v194, 5, v196
	v_ashrrev_i32_e32 v195, 31, v194
	v_lshlrev_b64 v[194:195], 10, v[194:195]
	v_lshl_add_u64 v[194:195], s[30:31], 0, v[194:195]
	v_lshl_add_u64 v[194:195], v[194:195], 0, v[184:185]
	global_load_dwordx4 v[96:99], v[194:195], off offset:128
	global_load_dwordx4 v[100:103], v[194:195], off offset:160
	global_load_dwordx4 v[104:107], v[194:195], off offset:192
	global_load_dwordx4 v[108:111], v[194:195], off offset:224
	s_sub_u32 s0, s68, s24
	s_subb_u32 s1, s69, s25
	s_add_u32 s0, s0, s78
	s_addc_u32 s1, s1, s79
	s_add_i32 m0, s5, 0x8000
	v_lshl_add_u64 v[198:199], v[116:117], 0, s[0:1]
	global_load_lds_dwordx4 v[198:199], off
	v_lshl_add_u64 v[198:199], v[112:113], 1, s[34:35]
	s_mov_b32 m0, s5
	s_nop 0
	global_load_lds_dwordx4 v[198:199], off
	v_lshl_add_u64 v[198:199], v[114:115], 1, s[34:35]
	s_add_i32 m0, s5, 0x2000
	s_nop 0
	global_load_lds_dwordx4 v[198:199], off
	v_mov_b32_e32 v66, v129
	s_nop 1
	v_permlane32_swap_b32_e32 v129, v66
	v_add_f32_e32 v64, v129, v66
	s_and_saveexec_b64 s[0:1], s[6:7]
	ds_write_b32 v122, v64
	s_or_b64 exec, exec, s[0:1]
	v_lshlrev_b32_e32 v64, 6, v121
	v_ashrrev_i32_e32 v65, 31, v64
	s_waitcnt lgkmcnt(0)
	v_add_u32_e32 v80, v119, v184
	v_lshl_add_u64 v[112:113], v[64:65], 2, s[12:13]
	ds_read_b128 v[64:67], v80
	ds_read_b128 v[68:71], v80 offset:32
	s_mov_b32 s5, 0
	v_mov_b32_e32 v130, 0
	v_mov_b32_e32 v131, 0
	s_waitcnt lgkmcnt(1)
	v_rcp_f32_e32 v72, v64
	v_rcp_f32_e32 v73, v65
	v_rcp_f32_e32 v74, v66
	v_rcp_f32_e32 v75, v67
	ds_read_b128 v[64:67], v80 offset:64
	s_waitcnt lgkmcnt(1)
	v_rcp_f32_e32 v68, v68
	v_rcp_f32_e32 v69, v69
	v_rcp_f32_e32 v70, v70
	v_rcp_f32_e32 v71, v71
	s_waitcnt lgkmcnt(0)
	v_rcp_f32_e32 v76, v64
	v_rcp_f32_e32 v77, v65
	v_rcp_f32_e32 v78, v66
	v_rcp_f32_e32 v79, v67
	ds_read_b128 v[64:67], v80 offset:96
	v_pk_mul_f32 v[48:49], v[48:49], v[72:73]
	v_pk_mul_f32 v[50:51], v[50:51], v[74:75]
	v_pk_mul_f32 v[32:33], v[32:33], v[72:73]
	v_pk_mul_f32 v[34:35], v[34:35], v[74:75]
	s_waitcnt lgkmcnt(0)
	v_rcp_f32_e32 v64, v64
	v_rcp_f32_e32 v65, v65
	v_rcp_f32_e32 v66, v66
	v_rcp_f32_e32 v67, v67
	v_pk_mul_f32 v[16:17], v[16:17], v[72:73]
	v_pk_mul_f32 v[18:19], v[18:19], v[74:75]
	v_pk_mul_f32 v[0:1], v[0:1], v[72:73]
	v_pk_mul_f32 v[2:3], v[2:3], v[74:75]
	global_store_dwordx4 v[112:113], v[48:51], off
	global_store_dwordx4 v[112:113], v[32:35], off offset:64
	global_store_dwordx4 v[112:113], v[16:19], off offset:128
	v_pk_mul_f32 v[48:49], v[52:53], v[68:69]
	v_pk_mul_f32 v[50:51], v[54:55], v[70:71]
	v_pk_mul_f32 v[32:33], v[36:37], v[68:69]
	v_pk_mul_f32 v[34:35], v[38:39], v[70:71]
	v_pk_mul_f32 v[16:17], v[20:21], v[68:69]
	v_pk_mul_f32 v[18:19], v[22:23], v[70:71]
	global_store_dwordx4 v[112:113], v[0:3], off offset:192
	global_store_dwordx4 v[112:113], v[48:51], off offset:16
	global_store_dwordx4 v[112:113], v[32:35], off offset:80
	v_pk_mul_f32 v[0:1], v[4:5], v[68:69]
	v_pk_mul_f32 v[2:3], v[6:7], v[70:71]
	v_pk_mul_f32 v[48:49], v[56:57], v[76:77]
	v_pk_mul_f32 v[50:51], v[58:59], v[78:79]
	v_pk_mul_f32 v[32:33], v[40:41], v[76:77]
	v_pk_mul_f32 v[34:35], v[42:43], v[78:79]
	global_store_dwordx4 v[112:113], v[16:19], off offset:144
	global_store_dwordx4 v[112:113], v[0:3], off offset:208
	global_store_dwordx4 v[112:113], v[48:51], off offset:32
	v_pk_mul_f32 v[16:17], v[24:25], v[76:77]
	v_pk_mul_f32 v[18:19], v[26:27], v[78:79]
	v_pk_mul_f32 v[0:1], v[8:9], v[76:77]
	v_pk_mul_f32 v[2:3], v[10:11], v[78:79]
	v_pk_mul_f32 v[48:49], v[60:61], v[64:65]
	v_pk_mul_f32 v[50:51], v[62:63], v[66:67]
	global_store_dwordx4 v[112:113], v[32:35], off offset:96
	global_store_dwordx4 v[112:113], v[16:19], off offset:160
	global_store_dwordx4 v[112:113], v[0:3], off offset:224
	v_pk_mul_f32 v[32:33], v[44:45], v[64:65]
	v_pk_mul_f32 v[34:35], v[46:47], v[66:67]
	v_pk_mul_f32 v[16:17], v[28:29], v[64:65]
	v_pk_mul_f32 v[18:19], v[30:31], v[66:67]
	v_pk_mul_f32 v[0:1], v[12:13], v[64:65]
	v_pk_mul_f32 v[2:3], v[14:15], v[66:67]
	v_mov_b32_e32 v4, v218
	global_store_dwordx4 v[112:113], v[48:51], off offset:48
	global_store_dwordx4 v[112:113], v[32:35], off offset:112
	global_store_dwordx4 v[112:113], v[16:19], off offset:176
	global_store_dwordx4 v[112:113], v[0:3], off offset:240
	v_mov_b32_e32 v14, v185
	v_and_b32_e32 v6, 31, v4
	v_and_b32_e32 v0, 0x3fffffc0, v4
	v_lshl_add_u32 v122, v0, 2, s4
	v_ashrrev_i32_e32 v0, 6, v4
	v_lshrrev_b32_e32 v7, 1, v4
	v_readfirstlane_b32 s0, v0
	v_lshl_or_b32 v0, v0, 5, v6
	v_ashrrev_i32_e32 v1, 31, v0
	v_lshlrev_b64 v[0:1], 10, v[0:1]
	v_and_b32_e32 v5, 63, v4
	v_lshl_add_u64 v[0:1], s[30:31], 0, v[0:1]
	v_and_b32_e32 v184, 16, v7
	v_lshl_add_u64 v[0:1], v[0:1], 0, v[184:185]
	s_lshl_b32 s1, s0, 10
	v_lshlrev_b32_e32 v8, 4, v5
	v_or_b32_e32 v0, s1, v8
	v_ashrrev_i32_e32 v1, 31, v0
	v_lshrrev_b32_e32 v1, 25, v1
	v_add_u32_e32 v1, v0, v1
	v_lshlrev_b32_e32 v9, 3, v5
	s_lshl_b32 s0, s0, 6
	v_ashrrev_i32_e32 v2, 7, v1
	v_and_b32_e32 v1, 0xffffff80, v1
	v_and_b32_e32 v3, 32, v4
	s_and_b32 s0, s0, 64
	v_and_b32_e32 v10, 24, v9
	v_sub_u32_e32 v0, v0, v1
	v_or3_b32 v3, v10, v3, s0
	s_ashr_i32 s0, s1, 8
	v_ashrrev_i32_e32 v0, 4, v0
	v_lshrrev_b32_e32 v1, 1, v2
	s_and_b32 s4, s0, 0x7ffff0
	s_lshr_b32 s0, s0, 1
	v_bitop3_b32 v0, v1, v0, 7 bitop3:0x6c
	v_bfe_u32 v1, v4, 2, 2
	s_and_b32 s0, s0, 4
	v_and_or_b32 v1, v7, 8, v1
	s_or_b32 s0, s4, s0
	v_or_b32_e32 v10, s0, v1
	s_add_i32 s0, s1, 0x2000
	s_ashr_i32 s0, s0, 8
	s_and_b32 s4, s0, 0x7ffff0
	s_lshr_b32 s0, s0, 1
	s_and_b32 s0, s0, 4
	s_or_b32 s0, s4, s0
	v_or_b32_e32 v1, s0, v1
	v_lshl_or_b32 v116, v1, 9, v3
	v_lshlrev_b32_e32 v1, 9, v2
	v_lshl_add_u32 v0, v0, 3, v1
	v_ashrrev_i32_e32 v1, 31, v0
	v_lshlrev_b64 v[0:1], 1, v[0:1]
	v_lshl_or_b32 v114, v10, 9, v3
	v_lshl_add_u64 v[2:3], s[68:69], 0, v[0:1]
	s_add_i32 s4, s1, 0
	v_lshl_add_u64 v[2:3], v[2:3], 0, s[78:79]
	s_add_i32 m0, s4, 0x8000
	v_ashrrev_i32_e32 v115, 31, v114
	v_lshl_add_u64 v[2:3], v[114:115], 1, s[34:35]
	s_mov_b32 m0, s4
	v_ashrrev_i32_e32 v117, 31, v116
	v_lshl_add_u64 v[2:3], v[116:117], 1, s[34:35]
	s_add_i32 m0, s4, 0x2000
	s_cmp_lg_u32 0, -1
	s_cselect_b32 s0, 0, 0
	v_lshlrev_b32_e32 v10, 1, v4
	v_lshlrev_b32_e32 v4, 3, v4
	s_add_i32 s1, s0, 0x8000
	v_and_b32_e32 v4, 0x70, v4
	v_lshl_add_u32 v124, v6, 7, s1
	s_movk_i32 s1, 0x60
	v_and_b32_e32 v3, 32, v10
	v_bitop3_b32 v128, v184, v4, s1 bitop3:0x36
	s_movk_i32 s1, 0x118
	v_and_b32_e32 v2, 0xc0, v8
	v_lshl_add_u64 v[118:119], s[24:25], 0, v[0:1]
	v_mov_b32_e32 v194, v0
	v_lshlrev_b32_e32 v195, 1, v114
	v_lshlrev_b32_e32 v196, 1, v116
	s_add_u32 s100, s24, 0x80
	s_addc_u32 s101, s25, 0
	v_and_or_b32 v0, v9, s1, v3
	v_mov_b32_e32 v15, v185
	v_bitop3_b32 v125, v7, v4, 16 bitop3:0x6c
	v_bitop3_b32 v126, v184, v4, 32 bitop3:0x36
	v_bitop3_b32 v127, v184, v4, 64 bitop3:0x36
	v_cmp_gt_u32_e64 s[6:7], 32, v5
	v_lshl_add_u32 v123, v6, 2, v122
	v_add3_u32 v129, v2, s0, v0
	v_mov_b32_e32 v0, v185
	v_mov_b32_e32 v1, v185
	v_mov_b32_e32 v2, v185
	v_mov_b32_e32 v3, v185
	v_mov_b32_e32 v4, v185
	v_mov_b32_e32 v5, v185
	v_mov_b32_e32 v6, v185
	v_mov_b32_e32 v7, v185
	v_mov_b32_e32 v8, v185
	v_mov_b32_e32 v9, v185
	v_mov_b32_e32 v10, v185
	v_mov_b32_e32 v11, v185
	v_mov_b32_e32 v12, v185
	v_mov_b32_e32 v13, v185
	v_mov_b64_e32 v[30:31], v[14:15]
	v_mov_b64_e32 v[46:47], v[14:15]
	v_mov_b64_e32 v[62:63], v[14:15]
	v_mov_b64_e32 v[28:29], v[12:13]
	v_mov_b64_e32 v[26:27], v[10:11]
	v_mov_b64_e32 v[24:25], v[8:9]
	v_mov_b64_e32 v[22:23], v[6:7]
	v_mov_b64_e32 v[20:21], v[4:5]
	v_mov_b64_e32 v[18:19], v[2:3]
	v_mov_b64_e32 v[16:17], v[0:1]
	v_mov_b64_e32 v[44:45], v[12:13]
	v_mov_b64_e32 v[42:43], v[10:11]
	v_mov_b64_e32 v[40:41], v[8:9]
	v_mov_b64_e32 v[38:39], v[6:7]
	v_mov_b64_e32 v[36:37], v[4:5]
	v_mov_b64_e32 v[34:35], v[2:3]
	v_mov_b64_e32 v[32:33], v[0:1]
	v_mov_b64_e32 v[60:61], v[12:13]
	v_mov_b64_e32 v[58:59], v[10:11]
	v_mov_b64_e32 v[56:57], v[8:9]
	v_mov_b64_e32 v[54:55], v[6:7]
	v_mov_b64_e32 v[52:53], v[4:5]
	v_mov_b64_e32 v[50:51], v[2:3]
	v_mov_b64_e32 v[48:49], v[0:1]
	v_mov_b32_e32 v160, 0x80000000
	v_mov_b32_e32 v161, 0x80000000
	v_mov_b32_e32 v162, 0x80000000
	v_mov_b32_e32 v163, 0x80000000
	v_mov_b32_e32 v164, 0x80000000
	v_mov_b32_e32 v165, 0x80000000
	v_mov_b32_e32 v166, 0x80000000
	v_mov_b32_e32 v167, 0x80000000
	v_mov_b32_e32 v168, 0x80000000
	v_mov_b32_e32 v169, 0x80000000
	v_mov_b32_e32 v170, 0x80000000
	v_mov_b32_e32 v171, 0x80000000
	v_mov_b32_e32 v172, 0x80000000
	v_mov_b32_e32 v173, 0x80000000
	v_mov_b32_e32 v174, 0x80000000
	v_mov_b32_e32 v175, 0x80000000
	v_readlane_b32 s54, v254, 48
	s_waitcnt vmcnt(16) lgkmcnt(0)
	s_barrier
	s_and_b32 s53, s5, 1
	v_add_u32_e32 v120, v124, v125
	ds_read_b128 v[132:135], v120 offset:0
	ds_read_b128 v[136:139], v120 offset:0x1000
	v_add_u32_e32 v210, v124, v126
	ds_read_b128 v[202:205], v210 offset:0
	ds_read_b128 v[206:209], v210 offset:0x1000
	s_cmp_eq_u32 s5, 31
	s_movk_i32 s0, 0x2000
	s_cbranch_scc1 .LBB0_152

.LBB0_152:
	v_add_u32_e32 v80, s0, v124
	s_waitcnt lgkmcnt(2)
	v_add_u32_e32 v120, v80, v127
	v_add_u32_e32 v150, v80, v128
	v_mfma_f32_32x32x16_bf16 v[80:95], v[132:135], v[96:99], v[160:175]
	ds_read_b128 v[132:135], v120 offset:0
	v_mfma_f32_32x32x16_bf16 v[64:79], v[136:139], v[96:99], v[160:175]
	ds_read_b128 v[136:139], v120 offset:0x1000
	s_waitcnt lgkmcnt(2)
	v_mfma_f32_32x32x16_bf16 v[80:95], v[202:205], v[100:103], v[80:95]
	ds_read_b128 v[140:143], v150 offset:0
	v_mfma_f32_32x32x16_bf16 v[64:79], v[206:209], v[100:103], v[64:79]
	ds_read_b128 v[146:149], v150 offset:0x1000
	s_waitcnt lgkmcnt(2)
	v_mfma_f32_32x32x16_bf16 v[80:95], v[132:135], v[104:107], v[80:95]
	s_waitcnt lgkmcnt(0)
	v_mfma_f32_32x32x16_bf16 v[64:79], v[136:139], v[104:107], v[64:79]
	v_mfma_f32_32x32x16_bf16 v[80:95], v[140:143], v[108:111], v[80:95]
	s_cmp_eq_u32 s5, 0
	s_cselect_b64 s[24:25], -1, 0
	s_cmp_lg_u32 s5, 0
	v_mfma_f32_32x32x16_bf16 v[64:79], v[146:149], v[108:111], v[64:79]
	s_nop 7
	v_max_f32_e32 v120, v80, v81
	v_max3_f32 v120, v120, v82, v83
	v_max3_f32 v120, v120, v84, v85
	v_max3_f32 v120, v120, v86, v87
	v_max3_f32 v120, v120, v88, v89
	v_max3_f32 v120, v120, v90, v91
	v_max3_f32 v120, v120, v92, v93
	v_max3_f32 v120, v120, v94, v95
	v_max3_f32 v120, v120, v64, v65
	v_max3_f32 v120, v120, v66, v67
	v_max3_f32 v120, v120, v68, v69
	v_max3_f32 v120, v120, v70, v71
	v_max3_f32 v120, v120, v72, v73
	v_max3_f32 v120, v120, v74, v75
	v_max3_f32 v120, v120, v76, v77
	v_max3_f32 v120, v120, v78, v79
	s_cbranch_scc0 .Lmx2_first
	v_cmp_ge_f32_e32 vcc, s62, v120
	s_cmp_lg_u64 vcc, exec
	s_mov_b64 s[34:35], 0
	s_mov_b64 s[30:31], 0
	s_cbranch_scc1 .Lmx2_slow
	v_mov_b32_e32 v132, 1.0
	s_branch .LBB0_164

.LBB0_164:
	v_exp_f32_e32 v80, v80
	v_exp_f32_e32 v81, v81
	v_exp_f32_e32 v82, v82
	v_exp_f32_e32 v83, v83
	v_exp_f32_e32 v84, v84
	v_exp_f32_e32 v120, v64
	v_exp_f32_e32 v85, v85
	v_add_f32_e32 v64, v81, v80
	v_exp_f32_e32 v86, v86
	v_add_f32_e32 v64, v82, v64
	v_exp_f32_e32 v87, v87
	v_add_f32_e32 v64, v83, v64
	v_exp_f32_e32 v88, v88
	v_add_f32_e32 v64, v84, v64
	v_exp_f32_e32 v89, v89
	v_add_f32_e32 v64, v85, v64
	v_exp_f32_e32 v90, v90
	v_add_f32_e32 v64, v86, v64
	v_exp_f32_e32 v91, v91
	v_add_f32_e32 v64, v87, v64
	v_exp_f32_e32 v92, v92
	v_add_f32_e32 v64, v88, v64
	v_exp_f32_e32 v93, v93
	v_add_f32_e32 v64, v89, v64
	v_exp_f32_e32 v94, v94
	v_add_f32_e32 v64, v90, v64
	v_exp_f32_e32 v95, v95
	v_add_f32_e32 v64, v91, v64
	v_add_f32_e32 v64, v92, v64
	v_exp_f32_e32 v65, v65
	v_add_f32_e32 v64, v93, v64
	v_exp_f32_e32 v133, v66
	v_add_f32_e32 v64, v94, v64
	v_exp_f32_e32 v134, v67
	v_add_f32_e32 v64, v95, v64
	v_exp_f32_e32 v135, v68
	v_add_f32_e32 v64, v120, v64
	v_exp_f32_e32 v136, v69
	v_add_f32_e32 v64, v65, v64
	v_exp_f32_e32 v137, v70
	v_add_f32_e32 v64, v133, v64
	v_exp_f32_e32 v138, v71
	v_add_f32_e32 v64, v134, v64
	v_exp_f32_e32 v139, v72
	v_add_f32_e32 v64, v135, v64
	v_exp_f32_e32 v140, v73
	v_add_f32_e32 v64, v136, v64
	v_exp_f32_e32 v141, v74
	v_add_f32_e32 v64, v137, v64
	v_exp_f32_e32 v142, v75
	v_add_f32_e32 v64, v138, v64
	v_exp_f32_e32 v143, v76
	v_add_f32_e32 v64, v139, v64
	v_exp_f32_e32 v146, v77
	v_add_f32_e32 v64, v140, v64
	v_exp_f32_e32 v147, v78
	v_add_f32_e32 v64, v141, v64
	v_exp_f32_e32 v148, v79
	v_add_f32_e32 v64, v142, v64
	v_add_f32_e32 v64, v143, v64
	v_add_f32_e32 v64, v146, v64
	v_add_f32_e32 v64, v147, v64
	v_add_f32_e32 v64, v148, v64
	s_add_i32 s5, s5, 1
	v_fma_f32 v131, v131, v132, v64
	v_cvt_pk_bf16_f32 v66, v80, v81
	v_cvt_pk_bf16_f32 v67, v82, v83
	v_cvt_pk_bf16_f32 v68, v84, v85
	v_cvt_pk_bf16_f32 v69, v86, v87
	v_cvt_pk_bf16_f32 v70, v88, v89
	v_cvt_pk_bf16_f32 v71, v90, v91
	v_cvt_pk_bf16_f32 v72, v92, v93
	v_cvt_pk_bf16_f32 v73, v94, v95
	v_cvt_pk_bf16_f32 v74, v120, v65
	v_cvt_pk_bf16_f32 v75, v133, v134
	v_cvt_pk_bf16_f32 v76, v135, v136
	v_cvt_pk_bf16_f32 v77, v137, v138
	v_cvt_pk_bf16_f32 v78, v139, v140
	v_cvt_pk_bf16_f32 v79, v141, v142
	v_cvt_pk_bf16_f32 v80, v143, v146
	v_cvt_pk_bf16_f32 v81, v147, v148
	s_nop 0
	v_permlane32_swap_b32_e32 v66, v68
	v_permlane32_swap_b32_e32 v67, v69
	v_permlane32_swap_b32_e32 v70, v72
	v_permlane32_swap_b32_e32 v71, v73
	v_permlane32_swap_b32_e32 v74, v76
	v_permlane32_swap_b32_e32 v75, v77
	v_permlane32_swap_b32_e32 v78, v80
	v_permlane32_swap_b32_e32 v79, v81
	v_lshl_add_u32 v65, s53, 14, v129
	ds_read_b64_tr_b16 v[82:83], v65 offset:0
	ds_read_b64_tr_b16 v[84:85], v65 offset:0x800
	ds_read_b64_tr_b16 v[86:87], v65 offset:0x1000
	ds_read_b64_tr_b16 v[88:89], v65 offset:0x1800
	ds_read_b64_tr_b16 v[90:91], v65 offset:0x2000
	ds_read_b64_tr_b16 v[92:93], v65 offset:0x2800
	ds_read_b64_tr_b16 v[132:133], v65 offset:0x3000
	ds_read_b64_tr_b16 v[134:135], v65 offset:0x3800
	ds_read_b64_tr_b16 v[136:137], v65 offset:0x200
	ds_read_b64_tr_b16 v[138:139], v65 offset:0xa00
	ds_read_b64_tr_b16 v[140:141], v65 offset:0x1200
	ds_read_b64_tr_b16 v[142:143], v65 offset:0x1a00
	ds_read_b64_tr_b16 v[146:147], v65 offset:0x2200
	ds_read_b64_tr_b16 v[148:149], v65 offset:0x2a00
	ds_read_b64_tr_b16 v[150:151], v65 offset:0x3200
	ds_read_b64_tr_b16 v[152:153], v65 offset:0x3a00
	s_waitcnt lgkmcnt(8)
	s_nop 0
	v_mfma_f32_32x32x16_bf16 v[48:63], v[66:69], v[82:85], v[48:63]
	ds_read_b64_tr_b16 v[82:83], v65 offset:0x400
	ds_read_b64_tr_b16 v[84:85], v65 offset:0xc00
	v_mfma_f32_32x32x16_bf16 v[48:63], v[70:73], v[86:89], v[48:63]
	ds_read_b64_tr_b16 v[86:87], v65 offset:0x1400
	ds_read_b64_tr_b16 v[88:89], v65 offset:0x1c00
	v_mfma_f32_32x32x16_bf16 v[48:63], v[74:77], v[90:93], v[48:63]
	ds_read_b64_tr_b16 v[90:91], v65 offset:0x2400
	ds_read_b64_tr_b16 v[92:93], v65 offset:0x2c00
	v_mfma_f32_32x32x16_bf16 v[48:63], v[78:81], v[132:135], v[48:63]
	ds_read_b64_tr_b16 v[132:133], v65 offset:0x3400
	ds_read_b64_tr_b16 v[134:135], v65 offset:0x3c00
	s_waitcnt lgkmcnt(8)
	v_mfma_f32_32x32x16_bf16 v[32:47], v[66:69], v[136:139], v[32:47]
	ds_read_b64_tr_b16 v[136:137], v65 offset:0x600
	ds_read_b64_tr_b16 v[138:139], v65 offset:0xe00
	v_mfma_f32_32x32x16_bf16 v[32:47], v[70:73], v[140:143], v[32:47]
	ds_read_b64_tr_b16 v[140:141], v65 offset:0x1600
	ds_read_b64_tr_b16 v[142:143], v65 offset:0x1e00
	v_mfma_f32_32x32x16_bf16 v[32:47], v[74:77], v[146:149], v[32:47]
	ds_read_b64_tr_b16 v[146:147], v65 offset:0x2600
	ds_read_b64_tr_b16 v[148:149], v65 offset:0x2e00
	v_mfma_f32_32x32x16_bf16 v[32:47], v[78:81], v[150:153], v[32:47]
	ds_read_b64_tr_b16 v[150:151], v65 offset:0x3600
	ds_read_b64_tr_b16 v[152:153], v65 offset:0x3e00
	s_waitcnt lgkmcnt(8)
	v_mfma_f32_32x32x16_bf16 v[16:31], v[66:69], v[82:85], v[16:31]
	s_waitcnt lgkmcnt(0)
	v_mfma_f32_32x32x16_bf16 v[16:31], v[70:73], v[86:89], v[16:31]
	v_mfma_f32_32x32x16_bf16 v[16:31], v[74:77], v[90:93], v[16:31]
	v_mfma_f32_32x32x16_bf16 v[16:31], v[78:81], v[132:135], v[16:31]
	v_mfma_f32_32x32x16_bf16 v[0:15], v[66:69], v[136:139], v[0:15]
	s_waitcnt vmcnt(0)
	s_add_i32 s67, s67, 0x8000
	s_cmp_eq_u32 s5, 32
	s_waitcnt vmcnt(0) lgkmcnt(0)
	s_barrier
	s_and_b32 s1, s5, 1
	s_lshl_b32 s1, s1, 13
	v_add3_u32 v120, v124, v125, s1
	v_add3_u32 v210, v124, v126, s1
	ds_read_b128 v[132:135], v120 offset:0
	ds_read_b128 v[136:139], v120 offset:0x1000
	ds_read_b128 v[202:205], v210 offset:0
	ds_read_b128 v[206:209], v210 offset:0x1000
	s_cmp_eq_u32 s5, 32
	v_mfma_f32_32x32x16_bf16 v[0:15], v[70:73], v[140:143], v[0:15]
	v_mfma_f32_32x32x16_bf16 v[0:15], v[74:77], v[146:149], v[0:15]
	v_mfma_f32_32x32x16_bf16 v[0:15], v[78:81], v[150:153], v[0:15]
	s_cbranch_scc1 .LBB0_166
	s_and_b32 s53, s5, 1
	s_cmp_eq_u32 s5, 31
	s_movk_i32 s0, 0x2000
	s_cbranch_scc0 .LBB0_151
	s_branch .LBB0_152

.LBB0_169:
	s_and_b32 s0, s64, 31
	s_lshl_b32 s0, s0, 6
	s_or_b32 s14, s14, s0
	s_mul_i32 s0, s15, 0x600
	s_mul_hi_u32 s1, s14, 0x600
	s_add_i32 s1, s1, s0
	s_mul_i32 s0, s14, 0x600
	s_add_u32 s0, s38, s0
	s_addc_u32 s1, s39, s1
	s_mul_hi_i32 s3, s2, 0xc0000
	s_mul_i32 s2, s2, 0xc0000
	v_mov_b32_e32 v158, v218
	s_add_u32 s4, s28, s2
	v_mov_b32_e32 v4, v218
	s_addc_u32 s5, s29, s3
	s_add_i32 s3, 0, 0x14000
	v_and_b32_e32 v0, 0x3fffffc0, v4
	v_lshl_add_u32 v159, v0, 2, s3
	v_ashrrev_i32_e32 v0, 6, v4
	v_and_b32_e32 v6, 31, v4
	v_readfirstlane_b32 s3, v0
	v_lshlrev_b32_e32 v0, 5, v0
	v_and_or_b32 v0, v0, 32, v6
	v_mul_u32_u24_e32 v0, 0x300, v0
	v_ashrrev_i32_e32 v2, 7, v4
	v_lshlrev_b32_e32 v184, 1, v0
	v_mul_lo_u32 v2, v2, s60
	v_lshl_add_u64 v[0:1], s[0:1], 0, v[184:185]
	v_ashrrev_i32_e32 v3, 31, v2
	v_lshl_add_u64 v[0:1], v[2:3], 1, v[0:1]
	v_lshrrev_b32_e32 v2, 1, v4
	v_and_b32_e32 v5, 63, v4
	v_and_b32_e32 v184, 16, v2
	v_lshl_add_u64 v[0:1], v[0:1], 0, v[184:185]
	s_lshl_b32 s6, s3, 10
	v_lshlrev_b32_e32 v3, 4, v5
	global_load_dwordx4 v[96:99], v[0:1], off
	global_load_dwordx4 v[100:103], v[0:1], off offset:32
	global_load_dwordx4 v[104:107], v[0:1], off offset:64
	global_load_dwordx4 v[108:111], v[0:1], off offset:96
	global_load_dwordx4 v[112:115], v[0:1], off offset:128
	global_load_dwordx4 v[116:119], v[0:1], off offset:160
	global_load_dwordx4 v[120:123], v[0:1], off offset:192
	global_load_dwordx4 v[124:127], v[0:1], off offset:224
	global_load_dwordx4 v[128:131], v[0:1], off offset:256
	global_load_dwordx4 v[132:135], v[0:1], off offset:288
	global_load_dwordx4 v[136:139], v[0:1], off offset:320
	global_load_dwordx4 v[140:143], v[0:1], off offset:352
	v_or_b32_e32 v0, s6, v3
	s_mov_b32 s0, 0x2aaaaaab
	v_mul_hi_i32 v1, v0, s0
	v_lshrrev_b32_e32 v7, 31, v1
	v_ashrrev_i32_e32 v1, 6, v1
	v_add_u32_e32 v1, v1, v7
	v_mul_i32_i24_e32 v7, 0x180, v1
	v_sub_u32_e32 v7, v0, v7
	v_ashrrev_i32_e32 v7, 4, v7
	v_lshrrev_b32_e32 v8, 1, v1
	v_bitop3_b32 v7, v8, v7, 7 bitop3:0x6c
	v_mul_i32_i24_e32 v1, 0xc0, v1
	v_lshl_add_u32 v146, v7, 3, v1
	v_add_u32_e32 v1, 0x2000, v0
	v_mul_hi_i32 v7, v1, s0
	v_lshrrev_b32_e32 v8, 31, v7
	v_ashrrev_i32_e32 v7, 6, v7
	v_add_u32_e32 v7, v7, v8
	v_mul_i32_i24_e32 v8, 0x180, v7
	v_sub_u32_e32 v1, v1, v8
	v_ashrrev_i32_e32 v1, 4, v1
	v_lshrrev_b32_e32 v8, 1, v7
	v_bitop3_b32 v1, v8, v1, 7 bitop3:0x6c
	v_mul_i32_i24_e32 v7, 0xc0, v7
	v_add_u32_e32 v0, 0x4000, v0
	v_lshl_add_u32 v148, v1, 3, v7
	v_mul_hi_i32 v1, v0, s0
	v_lshrrev_b32_e32 v7, 31, v1
	v_ashrrev_i32_e32 v1, 6, v1
	v_add_u32_e32 v1, v1, v7
	v_mul_i32_i24_e32 v7, 0x180, v1
	v_sub_u32_e32 v0, v0, v7
	v_ashrrev_i32_e32 v0, 4, v0
	v_lshrrev_b32_e32 v7, 1, v1
	v_bitop3_b32 v0, v7, v0, 7 bitop3:0x6c
	v_mul_i32_i24_e32 v1, 0xc0, v1
	v_lshlrev_b32_e32 v7, 3, v5
	s_lshl_b32 s0, s3, 6
	v_lshl_add_u32 v150, v0, 3, v1
	v_and_b32_e32 v1, 32, v4
	s_and_b32 s0, s0, 64
	v_and_b32_e32 v8, 24, v7
	v_or3_b32 v1, v8, v1, s0
	s_ashr_i32 s0, s6, 8
	s_and_b32 s1, s0, 0xfffff0
	s_lshr_b32 s0, s0, 1
	v_bfe_u32 v0, v4, 2, 2
	s_and_b32 s0, s0, 4
	v_and_or_b32 v0, v2, 8, v0
	s_or_b32 s0, s1, s0
	v_or_b32_e32 v8, s0, v0
	s_add_i32 s0, s6, 0x2000
	s_ashr_i32 s0, s0, 8
	s_lshl_b32 s2, s64, 2
	s_and_b32 s1, s0, 0xfffff0
	s_lshr_b32 s0, s0, 1
	s_and_b32 s2, s2, 28
	s_and_b32 s0, s0, 4
	s_or_b32 s0, s1, s0
	s_mulk_i32 s2, 0x6000
	v_or_b32_e32 v0, s0, v0
	s_add_u32 s0, s4, s2
	s_addc_u32 s1, s5, 0
	s_add_i32 s30, s6, 0
	v_ashrrev_i32_e32 v147, 31, v146
	v_mad_i32_i24 v152, v8, s60, v1
	v_mad_i32_i24 v154, v0, s60, v1
	s_add_i32 m0, s30, 0x8000
	v_lshl_add_u64 v[0:1], v[146:147], 1, s[0:1]
	v_ashrrev_i32_e32 v149, 31, v148
	s_waitcnt lgkmcnt(0)
	s_barrier
	global_load_lds_dwordx4 v[0:1], off
	v_lshl_add_u64 v[0:1], v[148:149], 1, s[0:1]
	s_add_i32 m0, s30, 0xa000
	v_ashrrev_i32_e32 v151, 31, v150
	global_load_lds_dwordx4 v[0:1], off
	v_lshl_add_u64 v[0:1], v[150:151], 1, s[0:1]
	s_add_i32 m0, s30, 0xc000
	v_ashrrev_i32_e32 v153, 31, v152
	global_load_lds_dwordx4 v[0:1], off
	v_lshl_add_u64 v[0:1], v[152:153], 1, s[0:1]
	s_mov_b32 m0, s30
	v_ashrrev_i32_e32 v155, 31, v154
	global_load_lds_dwordx4 v[0:1], off
	v_lshl_add_u64 v[0:1], v[154:155], 1, s[0:1]
	s_add_i32 m0, s30, 0x2000
	s_cmp_lg_u32 0, -1
	global_load_lds_dwordx4 v[0:1], off
	s_cselect_b32 s0, 0, 0
	s_add_i32 s1, s0, 0x8000
	v_lshlrev_b32_e32 v8, 1, v4
	v_lshlrev_b32_e32 v1, 3, v4
	v_mov_b32_e32 v4, s1
	s_movk_i32 s1, 0x180
	v_and_b32_e32 v1, 0x70, v1
	v_mad_u32_u24 v161, v6, s1, v4
	s_movk_i32 s1, 0x60
	v_and_b32_e32 v0, 32, v8
	v_bitop3_b32 v165, v184, v1, s1 bitop3:0x36
	s_movk_i32 s1, 0x118
	v_and_b32_e32 v3, 0xc0, v3
	v_and_or_b32 v0, v7, s1, v0
	v_add3_u32 v166, v3, s0, v0
	s_and_b32 s0, s64, 7
	v_mov_b32_e32 v14, v185
	v_mov_b32_e32 v15, v185
	v_bitop3_b32 v162, v2, v1, 16 bitop3:0x6c
	v_bitop3_b32 v163, v184, v1, 32 bitop3:0x36
	v_bitop3_b32 v164, v184, v1, 64 bitop3:0x36
	v_cmp_gt_u32_e64 s[6:7], 32, v5
	v_lshl_add_u32 v160, v6, 2, v159
	s_lshl_b32 s0, s0, 8
	v_mov_b32_e32 v0, v185
	v_mov_b32_e32 v1, v185
	v_mov_b32_e32 v2, v185
	v_mov_b32_e32 v3, v185
	v_mov_b32_e32 v4, v185
	v_mov_b32_e32 v5, v185
	v_mov_b32_e32 v6, v185
	v_mov_b32_e32 v7, v185
	v_mov_b32_e32 v8, v185
	v_mov_b32_e32 v9, v185
	v_mov_b32_e32 v10, v185
	v_mov_b32_e32 v11, v185
	v_mov_b32_e32 v12, v185
	v_mov_b32_e32 v13, v185
	v_mov_b64_e32 v[30:31], v[14:15]
	v_mov_b64_e32 v[46:47], v[14:15]
	v_mov_b64_e32 v[62:63], v[14:15]
	s_mov_b32 s31, 0
	s_or_b32 s34, s0, 64
	v_lshlrev_b32_e32 v197, 1, v146
	v_lshlrev_b32_e32 v198, 1, v148
	v_lshlrev_b32_e32 v199, 1, v150
	v_lshlrev_b32_e32 v200, 1, v152
	v_lshlrev_b32_e32 v201, 1, v154
	v_mov_b32_e32 v167, 0
	v_mov_b64_e32 v[28:29], v[12:13]
	v_mov_b64_e32 v[26:27], v[10:11]
	v_mov_b64_e32 v[24:25], v[8:9]
	v_mov_b64_e32 v[22:23], v[6:7]
	v_mov_b64_e32 v[20:21], v[4:5]
	v_mov_b64_e32 v[18:19], v[2:3]
	v_mov_b64_e32 v[16:17], v[0:1]
	v_mov_b64_e32 v[44:45], v[12:13]
	v_mov_b64_e32 v[42:43], v[10:11]
	v_mov_b64_e32 v[40:41], v[8:9]
	v_mov_b64_e32 v[38:39], v[6:7]
	v_mov_b64_e32 v[36:37], v[4:5]
	v_mov_b64_e32 v[34:35], v[2:3]
	v_mov_b64_e32 v[32:33], v[0:1]
	v_mov_b64_e32 v[60:61], v[12:13]
	v_mov_b64_e32 v[58:59], v[10:11]
	v_mov_b64_e32 v[56:57], v[8:9]
	v_mov_b64_e32 v[54:55], v[6:7]
	v_mov_b64_e32 v[52:53], v[4:5]
	v_mov_b64_e32 v[50:51], v[2:3]
	v_mov_b64_e32 v[48:49], v[0:1]
	v_mov_b32_e32 v168, 0
	s_waitcnt vmcnt(0) lgkmcnt(0)
	s_barrier
	s_and_b32 s35, s31, 1
	s_cmp_eq_u32 s31, 31
	s_cbranch_scc1 .LBB0_171
